# attention tile loop: all Q fragments of QK chains 1 and 2 prefetched before the tile barrier (no LDS read between the two chains)
# baseline (speedup 1.0000x reference)
; #define LAS __attribute__((address_space(3)))
; template <bool SHIFT> DI void phase_attn2(const Params& p, const Grp& G, int layer, LAS unsigned char* lds, int tid, int wave, int lane, int vcu, bool dry) {
;     ...
;         const int qb = u % NQB, bh = u / NQB, h = bh & 3, b = bh >> 2; const size_t seq0 = (size_t)b * G.S; const size_t qrow0 = seq0 + (size_t)qb * 256;
;         bf16x8 qf[2][4];
;         int lq = (int)__builtin_amdgcn_mbcnt_hi(~0u, __builtin_amdgcn_mbcnt_lo(~0u, 0u)); asm volatile("" : "+v"(lq));
; #pragma unroll
;         for (int rbq = 0; rbq < 2; ++rbq) { const bf16_t* qp = mix + (qrow0 + 64 * qg + 32 * rbq + (lq & 31)) * MIXW + h * 128 + c * 64 + 8 * (lq >> 5);
; #pragma unroll
;           for (int d0 = 0; d0 < 4; ++d0) qf[rbq][d0] = *(const bf16x8*)(qp + 16 * d0); }
;         LAS unsigned char* Qs = lds + AT2_QS + wave * 8192 + lane * 16;
;         const bf16_t* kg = rest + seq0 * RESTW + R_DK + h * 128; const bf16_t* vg = rest + seq0 * RESTW + R_DV + h * 128;
;         __syncthreads();
;     ...
;         { unsigned dfl = doff0; asm volatile("" : "+v"(dfl)); AT2_DMA(0, 0); }
; #pragma unroll
;         for (int rbq = 0; rbq < 2; ++rbq)
; #pragma unroll
;             for (int d0 = 0; d0 < 4; ++d0) *(LAS bf16x8*)(Qs + (rbq * 4 + d0) * 1024) = qf[rbq][d0];
;         asm volatile("s_waitcnt vmcnt(0)" ::: "memory");
;         __syncthreads();
.LBB0_377:
	s_abs_i32 s1, s58
	s_mul_hi_u32 s8, s1, s55
	s_mul_i32 s9, s8, s53
	s_ashr_i32 s0, s58, 31
	s_sub_i32 s1, s1, s9
	s_xor_b32 s0, s0, s54
	s_add_i32 s9, s8, 1
	s_sub_i32 s10, s1, s53
	s_cmp_ge_u32 s1, s53
	s_cselect_b32 s8, s9, s8
	s_cselect_b32 s1, s10, s1
	s_add_i32 s9, s8, 1
	s_cmp_ge_u32 s1, s53
	s_cselect_b32 s1, s9, s8
	s_xor_b32 s1, s1, s0
	s_sub_i32 s10, s1, s0
	s_mul_i32 s0, s10, s14
	s_sub_i32 s8, s58, s0
	s_ashr_i32 s0, s10, 2
	s_ashr_i32 s1, s0, 31
	v_readlane_b32 s9, v255, 40
	s_lshl_b64 s[0:1], s[0:1], s9
	s_ashr_i32 s9, s8, 31
	s_lshl_b64 s[8:9], s[8:9], 8
	s_add_u32 s40, s0, s8
	s_addc_u32 s41, s1, s9
	v_mov_b32_e32 v2, v245
	s_lshl_b32 s8, s10, 7
	s_and_b32 s59, s8, 0x180
	v_and_or_b32 v0, v2, 31, s13
	s_lshl_b32 s11, s59, 1
	v_ashrrev_i32_e32 v2, 2, v2
	s_add_u32 s8, s16, s11
	v_and_b32_e32 v2, -8, v2
	s_addc_u32 s9, s17, 0
	v_ashrrev_i32_e32 v3, 31, v2
	v_lshl_add_u64 v[2:3], v[2:3], 1, s[8:9]
	s_mulk_i32 s1, 0x1400
	s_mul_hi_u32 s9, s0, 0x1400
	v_or_b32_e32 v0, s40, v0
	v_mov_b32_e32 v1, s41
	s_mul_i32 s30, s0, 0x1400
	s_add_i32 s9, s9, s1
	v_lshlrev_b64 v[0:1], 11, v[0:1]
	s_add_u32 s0, s48, s30
	v_lshl_add_u64 v[16:17], v[2:3], 0, v[0:1]
	s_mov_b32 s8, 0x10000
	s_addc_u32 s1, s49, s9
	v_add_co_u32_e32 v28, vcc, s8, v16
	s_add_u32 s0, s0, s11
	s_nop 0
	v_addc_co_u32_e32 v29, vcc, 0, v17, vcc
	v_mov_b32_e32 v192, v219
	s_addc_u32 s1, s1, 0
	s_mov_b32 m0, s33
	global_load_dwordx4 v[0:3], v[16:17], off
	global_load_dwordx4 v[4:7], v[16:17], off offset:32
	global_load_dwordx4 v[8:11], v[16:17], off offset:64
	global_load_dwordx4 v[12:15], v[16:17], off offset:96
	s_nop 0
	global_load_dwordx4 v[16:19], v[28:29], off
	global_load_dwordx4 v[20:23], v[28:29], off offset:32
	global_load_dwordx4 v[24:27], v[28:29], off offset:64
	s_nop 0
	global_load_dwordx4 v[28:31], v[28:29], off offset:96
	s_barrier
	s_mov_b64 s[84:85], 0x400
	v_lshl_add_u64 v[34:35], s[0:1], 0, v[192:193]
	global_load_lds_dwordx4 v192, s[0:1]
	s_add_i32 m0, s33, 0x4000
	v_lshl_add_u64 v[34:35], v[34:35], 0, s[84:85]
	v_mov_b32_e32 v33, v193
	v_xad_u32 v32, v192, 16, v244
	global_load_lds_dwordx4 v[34:35], off
	s_add_i32 m0, s33, 0x400
	v_lshl_add_u64 v[36:37], s[0:1], 0, v[32:33]
	global_load_lds_dwordx4 v32, s[0:1]
	v_readlane_b32 s0, v254, 37
	v_lshl_add_u64 v[34:35], v[36:37], 0, s[84:85]
	s_mov_b32 m0, s0
	s_and_b32 s10, s10, 3
	global_load_lds_dwordx4 v[34:35], off
	s_lshl_b32 s10, s10, 8
	s_or_b32 s10, s30, s10
	v_mov_b32_e32 v64, 0
	s_add_u32 s30, s56, s10
	s_mov_b32 s8, 0
	v_mov_b32_e32 v222, v221
	s_mov_b32 s38, 0
	v_mov_b32_e32 v65, v64
	v_mov_b32_e32 v66, v64
	s_addc_u32 s31, s57, s9
	v_mov_b32_e32 v67, v64
	v_mov_b32_e32 v68, v64
	v_mov_b32_e32 v69, v64
	v_mov_b32_e32 v70, v64
	v_mov_b32_e32 v71, v64
	v_mov_b32_e32 v72, v64
	v_mov_b32_e32 v73, v64
	v_mov_b32_e32 v74, v64
	v_mov_b32_e32 v75, v64
	v_mov_b32_e32 v76, v64
	v_mov_b32_e32 v77, v64
	v_mov_b32_e32 v78, v64
	v_mov_b32_e32 v79, v64
	v_mov_b32_e32 v80, v64
	s_waitcnt vmcnt(0)
	ds_write_b128 v221, v[0:3]
	ds_write_b128 v221, v[4:7] offset:1024
	ds_write_b128 v221, v[8:11] offset:2048
	ds_write_b128 v221, v[12:15] offset:3072
	ds_write_b128 v221, v[16:19] offset:4096
	ds_write_b128 v221, v[20:23] offset:5120
	ds_write_b128 v221, v[24:27] offset:6144
	ds_write_b128 v221, v[28:31] offset:7168
	s_waitcnt vmcnt(0)
	v_mov_b32_e32 v81, v64
	v_mov_b32_e32 v82, v64
	v_mov_b32_e32 v83, v64
	v_mov_b32_e32 v84, v64
	v_mov_b32_e32 v85, v64
	v_mov_b32_e32 v86, v64
	v_mov_b32_e32 v87, v64
	v_mov_b32_e32 v88, v64
	v_mov_b32_e32 v89, v64
	v_mov_b32_e32 v90, v64
	v_mov_b32_e32 v91, v64
	v_mov_b32_e32 v92, v64
	v_mov_b32_e32 v93, v64
	v_mov_b32_e32 v94, v64
	v_mov_b32_e32 v95, v64
	v_mov_b32_e32 v96, v64
	v_mov_b32_e32 v97, v64
	v_mov_b32_e32 v98, v64
	v_mov_b32_e32 v99, v64
	v_mov_b32_e32 v100, v64
	v_mov_b32_e32 v101, v64
	v_mov_b32_e32 v102, v64
	v_mov_b32_e32 v103, v64
	v_mov_b32_e32 v104, v64
	v_mov_b32_e32 v105, v64
	v_mov_b32_e32 v106, v64
	v_mov_b32_e32 v107, v64
	v_mov_b32_e32 v108, v64
	v_mov_b32_e32 v109, v64
	v_mov_b32_e32 v110, v64
	v_mov_b32_e32 v111, v64
	v_mov_b32_e32 v112, v64
	v_mov_b32_e32 v113, v64
	v_mov_b32_e32 v114, v64
	v_mov_b32_e32 v115, v64
	v_mov_b32_e32 v116, v64
	v_mov_b32_e32 v117, v64
	v_mov_b32_e32 v118, v64
	v_mov_b32_e32 v119, v64
	v_mov_b32_e32 v120, v64
	v_mov_b32_e32 v121, v64
	v_mov_b32_e32 v122, v64
	v_mov_b32_e32 v123, v64
	v_mov_b32_e32 v124, v64
	v_mov_b32_e32 v125, v64
	v_mov_b32_e32 v126, v64
	v_mov_b32_e32 v127, v64
	v_mov_b32_e32 v0, v64
	v_mov_b32_e32 v1, v64
	v_mov_b32_e32 v2, v64
	v_mov_b32_e32 v3, v64
	v_mov_b32_e32 v4, v64
	v_mov_b32_e32 v5, v64
	v_mov_b32_e32 v6, v64
	v_mov_b32_e32 v7, v64
	v_mov_b32_e32 v8, v64
	v_mov_b32_e32 v9, v64
	v_mov_b32_e32 v10, v64
	v_mov_b32_e32 v11, v64
	v_mov_b32_e32 v12, v64
	v_mov_b32_e32 v13, v64
	v_mov_b32_e32 v14, v64
	v_mov_b32_e32 v15, v64
	v_mov_b32_e32 v16, v64
	v_mov_b32_e32 v17, v64
	v_mov_b32_e32 v18, v64
	v_mov_b32_e32 v19, v64
	v_mov_b32_e32 v20, v64
	v_mov_b32_e32 v21, v64
	v_mov_b32_e32 v22, v64
	v_mov_b32_e32 v23, v64
	v_mov_b32_e32 v24, v64
	v_mov_b32_e32 v25, v64
	v_mov_b32_e32 v26, v64
	v_mov_b32_e32 v27, v64
	v_mov_b32_e32 v28, v64
	v_mov_b32_e32 v29, v64
	v_mov_b32_e32 v30, v64
	v_mov_b32_e32 v31, v64
	v_mov_b32_e32 v32, v64
	v_mov_b32_e32 v33, v64
	v_mov_b32_e32 v34, v64
	v_mov_b32_e32 v35, v64
	v_mov_b32_e32 v36, v64
	v_mov_b32_e32 v37, v64
	v_mov_b32_e32 v38, v64
	v_mov_b32_e32 v39, v64
	v_mov_b32_e32 v40, v64
	v_mov_b32_e32 v41, v64
	v_mov_b32_e32 v42, v64
	v_mov_b32_e32 v43, v64
	v_mov_b32_e32 v44, v64
	v_mov_b32_e32 v45, v64
	v_mov_b32_e32 v46, v64
	v_mov_b32_e32 v47, v64
	v_mov_b32_e32 v48, v64
	v_mov_b32_e32 v49, v64
	v_mov_b32_e32 v50, v64
	v_mov_b32_e32 v51, v64
	v_mov_b32_e32 v52, v64
	v_mov_b32_e32 v53, v64
	v_mov_b32_e32 v54, v64
	v_mov_b32_e32 v55, v64
	v_mov_b32_e32 v56, v64
	v_mov_b32_e32 v57, v64
	v_mov_b32_e32 v58, v64
	v_mov_b32_e32 v59, v64
	v_mov_b32_e32 v60, v64
	v_mov_b32_e32 v61, v64
	v_mov_b32_e32 v62, v64
	v_mov_b32_e32 v63, v64
	v_mov_b32_e32 v164, v64
	v_mov_b32_e32 v165, v64
	v_xor_b32_e32 v236, 32, v217
	v_xor_b32_e32 v237, 64, v217
	v_xor_b32_e32 v238, 0x60, v217
	v_xor_b32_e32 v239, 32, v218
	v_xor_b32_e32 v240, 64, v218
	v_xor_b32_e32 v241, 0x60, v218
	v_xor_b32_e32 v248, 0x80, v218
	v_xor_b32_e32 v249, 0xa0, v218
	v_xor_b32_e32 v250, 0xc0, v218
	v_xor_b32_e32 v251, 0xe0, v218
	v_xad_u32 v252, v219, 16, v244
	s_waitcnt lgkmcnt(0)
	s_barrier
	ds_read_b128 v[132:135], v222
	ds_read_b128 v[136:139], v222 offset:1024
	ds_read_b128 v[140:143], v222 offset:2048
	ds_read_b128 v[228:231], v222 offset:3072
	ds_read_b128 v[174:177], v222 offset:4096
	ds_read_b128 v[178:181], v222 offset:5120
	ds_read_b128 v[182:185], v222 offset:6144
	ds_read_b128 v[224:227], v222 offset:7168
	s_branch .LBB0_379
; template <bool SHIFT> DI void phase_attn2(const Params& p, const Grp& G, int layer, LAS unsigned char* lds, int tid, int wave, int lane, int vcu, bool dry) {
;     ...
;             {
;                 f32x16 s0, s1; bf16x8 pa00, pa01, pa10, pa11; bf16x8 kfs[4], qfs[4];
;                 CHAIN(s0, 0, 0, true, true); CHAIN(s1, 0, 1, false, true);
.LBB0_378:
	s_waitcnt lgkmcnt(0)
	v_mfma_f32_32x32x16_bf16 v[144:159], v[128:131], v[132:135], 0
	v_mfma_f32_32x32x16_bf16 v[144:159], v[160:163], v[136:139], v[144:159]
	v_mfma_f32_32x32x16_bf16 v[144:159], v[166:169], v[140:143], v[144:159]
	v_mfma_f32_32x32x16_bf16 v[144:159], v[170:173], v[228:231], v[144:159]
	s_waitcnt lgkmcnt(0)
	v_mfma_f32_32x32x16_bf16 v[128:143], v[128:131], v[174:177], 0
	v_mfma_f32_32x32x16_bf16 v[128:143], v[160:163], v[178:181], v[128:143]
	v_mfma_f32_32x32x16_bf16 v[128:143], v[166:169], v[182:185], v[128:143]
	v_mfma_f32_32x32x16_bf16 v[128:143], v[170:173], v[224:227], v[128:143]
	ds_read_b128 v[170:173], v236 offset:8192
	ds_read_b128 v[228:231], v237 offset:8192
	ds_read_b128 v[232:235], v238 offset:8192
	s_nop 3
	v_exp_f32_e32 v144, v144
	v_exp_f32_e32 v145, v145
	v_exp_f32_e32 v146, v146
	v_exp_f32_e32 v147, v147
	v_exp_f32_e32 v148, v148
	v_exp_f32_e32 v149, v149
	v_exp_f32_e32 v150, v150
	v_exp_f32_e32 v188, v151
	v_exp_f32_e32 v208, v152
	v_exp_f32_e32 v206, v153
	v_exp_f32_e32 v204, v154
	v_exp_f32_e32 v202, v155
	v_exp_f32_e32 v200, v156
	v_exp_f32_e32 v198, v157
	v_exp_f32_e32 v196, v158
	v_exp_f32_e32 v190, v159
	v_exp_f32_e32 v189, v135
	v_add_f32_e32 v135, v145, v144
	v_exp_f32_e32 v128, v128
	v_exp_f32_e32 v129, v129
	v_exp_f32_e32 v130, v130
	v_exp_f32_e32 v131, v131
	v_exp_f32_e32 v132, v132
	v_exp_f32_e32 v133, v133
	v_exp_f32_e32 v134, v134
	v_add_f32_e32 v135, v146, v135
	v_add_f32_e32 v135, v147, v135
	v_add_f32_e32 v135, v148, v135
	v_add_f32_e32 v135, v149, v135
	v_cvt_pk_bf16_f32 v160, v144, v145
	v_cvt_pk_bf16_f32 v161, v146, v147
	v_cvt_pk_bf16_f32 v162, v148, v149
	v_cvt_pk_bf16_f32 v163, v150, v188
	v_exp_f32_e32 v209, v136
	v_exp_f32_e32 v207, v137
	v_exp_f32_e32 v205, v138
	v_exp_f32_e32 v203, v139
	v_exp_f32_e32 v201, v140
	v_exp_f32_e32 v199, v141
	v_exp_f32_e32 v197, v142
	v_exp_f32_e32 v191, v143
	v_add_f32_e32 v210, v150, v135
	v_cvt_pk_bf16_f32 v166, v128, v129
	v_cvt_pk_bf16_f32 v167, v130, v131
	v_cvt_pk_bf16_f32 v168, v132, v133
	v_cvt_pk_bf16_f32 v169, v134, v189
	ds_read_b128 v[144:147], v217 offset:8192
	v_add_f32_e32 v128, v129, v128
	v_add_f32_e32 v128, v130, v128
	v_add_f32_e32 v128, v131, v128
	v_add_f32_e32 v128, v132, v128
	v_add_f32_e32 v128, v133, v128
	v_add_f32_e32 v211, v134, v128
	s_waitcnt lgkmcnt(0)
	v_mfma_f32_32x32x16_bf16 v[128:143], v[144:147], v[174:177], 0
	v_mfma_f32_32x32x16_bf16 v[128:143], v[170:173], v[178:181], v[128:143]
	v_mfma_f32_32x32x16_bf16 v[128:143], v[228:231], v[182:185], v[128:143]
	v_mfma_f32_32x32x16_bf16 v[128:143], v[232:235], v[224:227], v[128:143]
	ds_read_b128 v[148:151], v222
	ds_read_b128 v[174:177], v222 offset:1024
	ds_read_b128 v[178:181], v222 offset:2048
	ds_read_b128 v[182:185], v222 offset:3072
	s_waitcnt lgkmcnt(0)
	v_mfma_f32_32x32x16_bf16 v[144:159], v[144:147], v[148:151], 0
	v_mfma_f32_32x32x16_bf16 v[144:159], v[170:173], v[174:177], v[144:159]
	v_mfma_f32_32x32x16_bf16 v[144:159], v[228:231], v[178:181], v[144:159]
	v_mfma_f32_32x32x16_bf16 v[144:159], v[232:235], v[182:185], v[144:159]
	s_nop 4
	ds_read_b64_tr_b16 v[170:171], v218 offset:16384
	ds_read_b64_tr_b16 v[172:173], v239 offset:18432
	ds_read_b64_tr_b16 v[174:175], v240 offset:16384
	ds_read_b64_tr_b16 v[176:177], v241 offset:18432
	ds_read_b64_tr_b16 v[178:179], v248 offset:16384
	ds_read_b64_tr_b16 v[180:181], v249 offset:18432
	ds_read_b64_tr_b16 v[182:183], v250 offset:16384
	ds_read_b64_tr_b16 v[184:185], v251 offset:18432
	v_exp_f32_e32 v144, v144
	s_waitcnt lgkmcnt(6)
	v_mfma_f32_32x32x16_bf16 v[112:127], v[160:163], v[170:173], v[112:127]
	v_exp_f32_e32 v145, v145
	v_exp_f32_e32 v146, v146
	v_exp_f32_e32 v147, v147
	v_exp_f32_e32 v148, v148
	v_exp_f32_e32 v149, v149
	v_mfma_f32_32x32x16_bf16 v[0:15], v[166:169], v[170:173], v[0:15]
	v_exp_f32_e32 v170, v151
	v_exp_f32_e32 v172, v154
	s_waitcnt lgkmcnt(4)
	v_mfma_f32_32x32x16_bf16 v[96:111], v[160:163], v[174:177], v[96:111]
	v_mfma_f32_32x32x16_bf16 v[16:31], v[166:169], v[174:177], v[16:31]
	v_exp_f32_e32 v174, v153
	v_exp_f32_e32 v176, v156
	s_waitcnt lgkmcnt(2)
	v_mfma_f32_32x32x16_bf16 v[80:95], v[160:163], v[178:181], v[80:95]
	v_mfma_f32_32x32x16_bf16 v[32:47], v[166:169], v[178:181], v[32:47]
	v_exp_f32_e32 v178, v155
	v_exp_f32_e32 v180, v158
	s_waitcnt lgkmcnt(0)
	v_mfma_f32_32x32x16_bf16 v[64:79], v[160:163], v[182:185], v[64:79]
	v_add_f32_e32 v160, v145, v144
	v_add_f32_e32 v160, v146, v160
	v_add_f32_e32 v160, v147, v160
	v_add_f32_e32 v160, v148, v160
	v_add_f32_e32 v186, v149, v160
	v_cvt_pk_bf16_f32 v144, v144, v145
	v_mfma_f32_32x32x16_bf16 v[48:63], v[166:169], v[182:185], v[48:63]
	v_exp_f32_e32 v166, v150
	v_exp_f32_e32 v168, v152
	v_exp_f32_e32 v182, v157
	v_exp_f32_e32 v184, v159
	v_cvt_pk_bf16_f32 v145, v146, v147
	v_cvt_pk_bf16_f32 v146, v148, v149
	s_nop 0
	ds_read_b64_tr_b16 v[160:161], v218 offset:20480
	ds_read_b64_tr_b16 v[162:163], v239 offset:22528
	ds_read_b64_tr_b16 v[156:157], v240 offset:20480
	ds_read_b64_tr_b16 v[158:159], v241 offset:22528
	ds_read_b64_tr_b16 v[152:153], v248 offset:20480
	ds_read_b64_tr_b16 v[154:155], v249 offset:22528
	ds_read_b64_tr_b16 v[148:149], v250 offset:20480
	ds_read_b64_tr_b16 v[150:151], v251 offset:22528
	v_exp_f32_e32 v223, v128
	v_exp_f32_e32 v224, v129
	v_exp_f32_e32 v225, v130
	v_exp_f32_e32 v226, v131
	v_exp_f32_e32 v227, v132
	v_add_f32_e32 v128, v224, v223
	v_exp_f32_e32 v228, v133
	v_exp_f32_e32 v167, v134
	v_exp_f32_e32 v171, v135
	v_cvt_pk_bf16_f32 v132, v208, v206
	v_cvt_pk_bf16_f32 v133, v204, v202
	v_cvt_pk_bf16_f32 v134, v200, v198
	v_cvt_pk_bf16_f32 v135, v196, v190
	v_add_f32_e32 v128, v225, v128
	v_exp_f32_e32 v169, v136
	v_exp_f32_e32 v175, v137
	v_exp_f32_e32 v173, v138
	v_exp_f32_e32 v179, v139
	v_cvt_pk_bf16_f32 v136, v209, v207
	v_cvt_pk_bf16_f32 v137, v205, v203
	v_cvt_pk_bf16_f32 v138, v201, v199
	v_cvt_pk_bf16_f32 v139, v197, v191
	v_add_f32_e32 v128, v226, v128
	v_add_f32_e32 v128, v227, v128
	v_add_f32_e32 v187, v228, v128
	v_pk_add_f32 v[128:129], v[188:189], v[210:211]
	s_waitcnt lgkmcnt(6)
; #define LAS __attribute__((address_space(3)))
; #define SB() __builtin_amdgcn_sched_barrier(0)
; #define BLOAD(B_, ks_) do { asm volatile("" : "+v"(v0l)); _Pragma("unroll") for (int cb = 0; cb < 4; ++cb) B_[cb] = BFRAG(ks_, cb); SB(); } while (0)
; #define PVMMA(B_, pA_, pB_) do { _Pragma("unroll") for (int cb = 0; cb < 4; ++cb) { o[0][cb] = MFMA32(pA_, B_[cb], o[0][cb]); o[1][cb] = MFMA32(pB_, B_[cb], o[1][cb]); } } while (0)
; template <bool SHIFT> DI void phase_attn2(const Params& p, const Grp& G, int layer, LAS unsigned char* lds, int tid, int wave, int lane, int vcu, bool dry) {
;     ...
;         for (int t = 0; t < NT; ++t) {
;             unsigned dfl = doff0; asm volatile("" : "+v"(dfl));
;             if (t + 1 < NT) AT2_DMA(t + 1, (t + 1) & 1);
;             const LAS unsigned char* Kt = lds + (t & 1) * AT2_BUF; const LAS unsigned char* Vt = Kt + AT2_TILE;
;             int k0l = k0, v0l = v0; asm volatile("" : "+v"(k0l), "+v"(v0l));
;     ...
;                 BLOAD(B, 3);
;                 PVMMA(B, pb01, pb11);
;                 SB();
;             }
;     ...
;             asm volatile("s_waitcnt vmcnt(0)" ::: "memory");
;             __syncthreads();
	v_mfma_f32_32x32x16_bf16 v[112:127], v[132:135], v[160:163], v[112:127]
	v_add_f32_e64 v128, v208, v128
	v_add_f32_e64 v129, v209, v129
	v_exp_f32_e32 v177, v140
	v_pk_add_f32 v[128:129], v[206:207], v[128:129]
	v_exp_f32_e32 v183, v141
	v_pk_add_f32 v[128:129], v[204:205], v[128:129]
	v_exp_f32_e32 v181, v142
	v_pk_add_f32 v[128:129], v[202:203], v[128:129]
	s_waitcnt lgkmcnt(4)
	v_mfma_f32_32x32x16_bf16 v[96:111], v[132:135], v[156:159], v[96:111]
	v_exp_f32_e32 v185, v143
	v_pk_add_f32 v[128:129], v[200:201], v[128:129]
	v_cvt_pk_bf16_f32 v147, v166, v170
	v_pk_add_f32 v[128:129], v[198:199], v[128:129]
	v_cvt_pk_bf16_f32 v130, v176, v182
	v_pk_add_f32 v[128:129], v[196:197], v[128:129]
	v_cvt_pk_bf16_f32 v131, v180, v184
	s_waitcnt lgkmcnt(2)
	v_mfma_f32_32x32x16_bf16 v[80:95], v[132:135], v[152:155], v[80:95]
	v_add_f32_e64 v128, v190, v128
	v_add_f32_e64 v129, v191, v129
	v_add_f32_e64 v140, v164, v128
	v_add_f32_e64 v141, v165, v129
	v_cvt_pk_bf16_f32 v128, v168, v174
	v_cvt_pk_bf16_f32 v129, v172, v178
	s_waitcnt lgkmcnt(0)
	v_mfma_f32_32x32x16_bf16 v[64:79], v[132:135], v[148:151], v[64:79]
	v_add_f32_e64 v132, v166, v186
	v_add_f32_e64 v133, v167, v187
	v_cvt_pk_bf16_f32 v134, v227, v228
	v_add_f32_e64 v132, v170, v132
	v_add_f32_e64 v133, v171, v133
	v_cvt_pk_bf16_f32 v135, v167, v171
	v_pk_add_f32 v[132:133], v[168:169], v[132:133]
	s_nop 0
	v_pk_add_f32 v[132:133], v[174:175], v[132:133]
	v_mfma_f32_32x32x16_bf16 v[0:15], v[136:139], v[160:163], v[0:15]
	v_add_f32_e64 v132, v172, v132
	v_add_f32_e64 v133, v173, v133
	v_add_f32_e64 v132, v178, v132
	v_add_f32_e64 v133, v179, v133
	v_add_f32_e64 v132, v176, v132
	v_add_f32_e64 v133, v177, v133
	v_pk_add_f32 v[132:133], v[182:183], v[132:133]
	v_mfma_f32_32x32x16_bf16 v[16:31], v[136:139], v[156:159], v[16:31]
	v_add_f32_e64 v132, v180, v132
	v_add_f32_e64 v133, v181, v133
	v_add_f32_e64 v142, v184, v132
	v_add_f32_e64 v143, v185, v133
	v_cvt_pk_bf16_f32 v132, v223, v224
	v_cvt_pk_bf16_f32 v133, v225, v226
	v_mfma_f32_32x32x16_bf16 v[32:47], v[136:139], v[152:155], v[32:47]
	v_mfma_f32_32x32x16_bf16 v[48:63], v[136:139], v[148:151], v[48:63]
	v_cvt_pk_bf16_f32 v136, v169, v175
	v_cvt_pk_bf16_f32 v137, v173, v179
	v_cvt_pk_bf16_f32 v138, v177, v183
	v_cvt_pk_bf16_f32 v139, v181, v185
	s_nop 0
	ds_read_b64_tr_b16 v[148:149], v218 offset:24576
	ds_read_b64_tr_b16 v[150:151], v239 offset:26624
	ds_read_b64_tr_b16 v[152:153], v240 offset:24576
	ds_read_b64_tr_b16 v[154:155], v241 offset:26624
	ds_read_b64_tr_b16 v[156:157], v248 offset:24576
	ds_read_b64_tr_b16 v[158:159], v249 offset:26624
	ds_read_b64_tr_b16 v[160:161], v250 offset:24576
	ds_read_b64_tr_b16 v[162:163], v251 offset:26624
	s_waitcnt lgkmcnt(6)
	v_mfma_f32_32x32x16_bf16 v[112:127], v[144:147], v[148:151], v[112:127]
	v_add_f32_e64 v164, v140, v142
	v_add_f32_e64 v165, v141, v143
	v_mfma_f32_32x32x16_bf16 v[0:15], v[132:135], v[148:151], v[0:15]
	s_waitcnt lgkmcnt(4)
	v_mfma_f32_32x32x16_bf16 v[96:111], v[144:147], v[152:155], v[96:111]
	v_mfma_f32_32x32x16_bf16 v[16:31], v[132:135], v[152:155], v[16:31]
	s_waitcnt lgkmcnt(2)
	v_mfma_f32_32x32x16_bf16 v[80:95], v[144:147], v[156:159], v[80:95]
	v_mfma_f32_32x32x16_bf16 v[32:47], v[132:135], v[156:159], v[32:47]
	s_waitcnt lgkmcnt(0)
	v_mfma_f32_32x32x16_bf16 v[64:79], v[144:147], v[160:163], v[64:79]
	v_mfma_f32_32x32x16_bf16 v[48:63], v[132:135], v[160:163], v[48:63]
	s_nop 0
	ds_read_b64_tr_b16 v[132:133], v218 offset:28672
	ds_read_b64_tr_b16 v[134:135], v239 offset:30720
	ds_read_b64_tr_b16 v[140:141], v240 offset:28672
	ds_read_b64_tr_b16 v[142:143], v241 offset:30720
	ds_read_b64_tr_b16 v[144:145], v248 offset:28672
	ds_read_b64_tr_b16 v[146:147], v249 offset:30720
	ds_read_b64_tr_b16 v[148:149], v250 offset:28672
	ds_read_b64_tr_b16 v[150:151], v251 offset:30720
	s_waitcnt lgkmcnt(6)
	v_mfma_f32_32x32x16_bf16 v[112:127], v[128:131], v[132:135], v[112:127]
	v_mfma_f32_32x32x16_bf16 v[0:15], v[136:139], v[132:135], v[0:15]
	ds_read_b128 v[132:135], v222
	ds_read_b128 v[228:231], v222 offset:3072
	s_waitcnt lgkmcnt(6)
	v_mfma_f32_32x32x16_bf16 v[96:111], v[128:131], v[140:143], v[96:111]
	v_mfma_f32_32x32x16_bf16 v[16:31], v[136:139], v[140:143], v[16:31]
	ds_read_b128 v[140:143], v222 offset:2048
	s_waitcnt lgkmcnt(5)
	v_mfma_f32_32x32x16_bf16 v[80:95], v[128:131], v[144:147], v[80:95]
	v_mfma_f32_32x32x16_bf16 v[32:47], v[136:139], v[144:147], v[32:47]
	s_waitcnt lgkmcnt(3)
	v_mfma_f32_32x32x16_bf16 v[64:79], v[128:131], v[148:151], v[64:79]
	v_mfma_f32_32x32x16_bf16 v[48:63], v[136:139], v[148:151], v[48:63]
	ds_read_b128 v[136:139], v222 offset:1024
	ds_read_b128 v[174:177], v222 offset:4096
	ds_read_b128 v[178:181], v222 offset:5120
	ds_read_b128 v[182:185], v222 offset:6144
	ds_read_b128 v[224:227], v222 offset:7168
	s_waitcnt vmcnt(0)
	s_add_u32 s30, s30, 0x50000
	s_addc_u32 s31, s31, 0
	s_cmp_eq_u32 s45, s38
	s_mov_b32 s8, s39
	s_barrier
	s_cbranch_scc1 .LBB0_383
	s_branch .Lat2_top_O

; template <bool SHIFT> DI void phase_attn2(const Params& p, const Grp& G, int layer, LAS unsigned char* lds, int tid, int wave, int lane, int vcu, bool dry) {
;     ...
;             {
;                 f32x16 s0, s1; bf16x8 pa00, pa01, pa10, pa11; bf16x8 kfs[4], qfs[4];
;                 CHAIN(s0, 0, 0, true, true); CHAIN(s1, 0, 1, false, true);
.Lat2_body_O:
	s_waitcnt lgkmcnt(0)
	v_mfma_f32_32x32x16_bf16 v[144:159], v[128:131], v[132:135], 0
	v_mfma_f32_32x32x16_bf16 v[144:159], v[160:163], v[136:139], v[144:159]
	v_mfma_f32_32x32x16_bf16 v[144:159], v[166:169], v[140:143], v[144:159]
	v_mfma_f32_32x32x16_bf16 v[144:159], v[170:173], v[228:231], v[144:159]
	s_waitcnt lgkmcnt(0)
	v_mfma_f32_32x32x16_bf16 v[128:143], v[128:131], v[174:177], 0
	v_mfma_f32_32x32x16_bf16 v[128:143], v[160:163], v[178:181], v[128:143]
	v_mfma_f32_32x32x16_bf16 v[128:143], v[166:169], v[182:185], v[128:143]
	v_mfma_f32_32x32x16_bf16 v[128:143], v[170:173], v[224:227], v[128:143]
	ds_read_b128 v[170:173], v236 offset:40960
	ds_read_b128 v[228:231], v237 offset:40960
	ds_read_b128 v[232:235], v238 offset:40960
	s_nop 3
	v_exp_f32_e32 v144, v144
	v_exp_f32_e32 v145, v145
	v_exp_f32_e32 v146, v146
	v_exp_f32_e32 v147, v147
	v_exp_f32_e32 v148, v148
	v_exp_f32_e32 v149, v149
	v_exp_f32_e32 v150, v150
	v_exp_f32_e32 v188, v151
	v_exp_f32_e32 v208, v152
	v_exp_f32_e32 v206, v153
	v_exp_f32_e32 v204, v154
	v_exp_f32_e32 v202, v155
	v_exp_f32_e32 v200, v156
	v_exp_f32_e32 v198, v157
	v_exp_f32_e32 v196, v158
	v_exp_f32_e32 v190, v159
	v_exp_f32_e32 v189, v135
	v_add_f32_e32 v135, v145, v144
	v_exp_f32_e32 v128, v128
	v_exp_f32_e32 v129, v129
	v_exp_f32_e32 v130, v130
	v_exp_f32_e32 v131, v131
	v_exp_f32_e32 v132, v132
	v_exp_f32_e32 v133, v133
	v_exp_f32_e32 v134, v134
	v_add_f32_e32 v135, v146, v135
	v_add_f32_e32 v135, v147, v135
	v_add_f32_e32 v135, v148, v135
	v_add_f32_e32 v135, v149, v135
	v_cvt_pk_bf16_f32 v160, v144, v145
	v_cvt_pk_bf16_f32 v161, v146, v147
	v_cvt_pk_bf16_f32 v162, v148, v149
	v_cvt_pk_bf16_f32 v163, v150, v188
	v_exp_f32_e32 v209, v136
	v_exp_f32_e32 v207, v137
	v_exp_f32_e32 v205, v138
	v_exp_f32_e32 v203, v139
	v_exp_f32_e32 v201, v140
	v_exp_f32_e32 v199, v141
	v_exp_f32_e32 v197, v142
	v_exp_f32_e32 v191, v143
	v_add_f32_e32 v210, v150, v135
	v_cvt_pk_bf16_f32 v166, v128, v129
	v_cvt_pk_bf16_f32 v167, v130, v131
	v_cvt_pk_bf16_f32 v168, v132, v133
	v_cvt_pk_bf16_f32 v169, v134, v189
	ds_read_b128 v[144:147], v217 offset:40960
	v_add_f32_e32 v128, v129, v128
	v_add_f32_e32 v128, v130, v128
	v_add_f32_e32 v128, v131, v128
	v_add_f32_e32 v128, v132, v128
	v_add_f32_e32 v128, v133, v128
	v_add_f32_e32 v211, v134, v128
	s_waitcnt lgkmcnt(0)
	v_mfma_f32_32x32x16_bf16 v[128:143], v[144:147], v[174:177], 0
	v_mfma_f32_32x32x16_bf16 v[128:143], v[170:173], v[178:181], v[128:143]
	v_mfma_f32_32x32x16_bf16 v[128:143], v[228:231], v[182:185], v[128:143]
	v_mfma_f32_32x32x16_bf16 v[128:143], v[232:235], v[224:227], v[128:143]
	ds_read_b128 v[148:151], v222
	ds_read_b128 v[174:177], v222 offset:1024
	ds_read_b128 v[178:181], v222 offset:2048
	ds_read_b128 v[182:185], v222 offset:3072
	s_waitcnt lgkmcnt(0)
	v_mfma_f32_32x32x16_bf16 v[144:159], v[144:147], v[148:151], 0
	v_mfma_f32_32x32x16_bf16 v[144:159], v[170:173], v[174:177], v[144:159]
	v_mfma_f32_32x32x16_bf16 v[144:159], v[228:231], v[178:181], v[144:159]
	v_mfma_f32_32x32x16_bf16 v[144:159], v[232:235], v[182:185], v[144:159]
	s_nop 4
	ds_read_b64_tr_b16 v[170:171], v218 offset:49152
	ds_read_b64_tr_b16 v[172:173], v239 offset:51200
	ds_read_b64_tr_b16 v[174:175], v240 offset:49152
	ds_read_b64_tr_b16 v[176:177], v241 offset:51200
	ds_read_b64_tr_b16 v[178:179], v248 offset:49152
	ds_read_b64_tr_b16 v[180:181], v249 offset:51200
	ds_read_b64_tr_b16 v[182:183], v250 offset:49152
	ds_read_b64_tr_b16 v[184:185], v251 offset:51200
	v_exp_f32_e32 v144, v144
	s_waitcnt lgkmcnt(6)
	v_mfma_f32_32x32x16_bf16 v[112:127], v[160:163], v[170:173], v[112:127]
	v_exp_f32_e32 v145, v145
	v_exp_f32_e32 v146, v146
	v_exp_f32_e32 v147, v147
	v_exp_f32_e32 v148, v148
	v_exp_f32_e32 v149, v149
	v_mfma_f32_32x32x16_bf16 v[0:15], v[166:169], v[170:173], v[0:15]
	v_exp_f32_e32 v170, v151
	v_exp_f32_e32 v172, v154
	s_waitcnt lgkmcnt(4)
	v_mfma_f32_32x32x16_bf16 v[96:111], v[160:163], v[174:177], v[96:111]
	v_mfma_f32_32x32x16_bf16 v[16:31], v[166:169], v[174:177], v[16:31]
	v_exp_f32_e32 v174, v153
	v_exp_f32_e32 v176, v156
	s_waitcnt lgkmcnt(2)
	v_mfma_f32_32x32x16_bf16 v[80:95], v[160:163], v[178:181], v[80:95]
	v_mfma_f32_32x32x16_bf16 v[32:47], v[166:169], v[178:181], v[32:47]
	v_exp_f32_e32 v178, v155
	v_exp_f32_e32 v180, v158
	s_waitcnt lgkmcnt(0)
	v_mfma_f32_32x32x16_bf16 v[64:79], v[160:163], v[182:185], v[64:79]
	v_add_f32_e32 v160, v145, v144
	v_add_f32_e32 v160, v146, v160
	v_add_f32_e32 v160, v147, v160
	v_add_f32_e32 v160, v148, v160
	v_add_f32_e32 v186, v149, v160
	v_cvt_pk_bf16_f32 v144, v144, v145
	v_mfma_f32_32x32x16_bf16 v[48:63], v[166:169], v[182:185], v[48:63]
	v_exp_f32_e32 v166, v150
	v_exp_f32_e32 v168, v152
	v_exp_f32_e32 v182, v157
	v_exp_f32_e32 v184, v159
	v_cvt_pk_bf16_f32 v145, v146, v147
	v_cvt_pk_bf16_f32 v146, v148, v149
	s_nop 0
	ds_read_b64_tr_b16 v[160:161], v218 offset:53248
	ds_read_b64_tr_b16 v[162:163], v239 offset:55296
	ds_read_b64_tr_b16 v[156:157], v240 offset:53248
	ds_read_b64_tr_b16 v[158:159], v241 offset:55296
	ds_read_b64_tr_b16 v[152:153], v248 offset:53248
	ds_read_b64_tr_b16 v[154:155], v249 offset:55296
	ds_read_b64_tr_b16 v[148:149], v250 offset:53248
	ds_read_b64_tr_b16 v[150:151], v251 offset:55296
	v_exp_f32_e32 v223, v128
	v_exp_f32_e32 v224, v129
	v_exp_f32_e32 v225, v130
	v_exp_f32_e32 v226, v131
	v_exp_f32_e32 v227, v132
	v_add_f32_e32 v128, v224, v223
	v_exp_f32_e32 v228, v133
	v_exp_f32_e32 v167, v134
	v_exp_f32_e32 v171, v135
	v_cvt_pk_bf16_f32 v132, v208, v206
	v_cvt_pk_bf16_f32 v133, v204, v202
	v_cvt_pk_bf16_f32 v134, v200, v198
	v_cvt_pk_bf16_f32 v135, v196, v190
	v_add_f32_e32 v128, v225, v128
	v_exp_f32_e32 v169, v136
	v_exp_f32_e32 v175, v137
	v_exp_f32_e32 v173, v138
	v_exp_f32_e32 v179, v139
	v_cvt_pk_bf16_f32 v136, v209, v207
	v_cvt_pk_bf16_f32 v137, v205, v203
	v_cvt_pk_bf16_f32 v138, v201, v199
	v_cvt_pk_bf16_f32 v139, v197, v191
	v_add_f32_e32 v128, v226, v128
	v_add_f32_e32 v128, v227, v128
	v_add_f32_e32 v187, v228, v128
	v_pk_add_f32 v[128:129], v[188:189], v[210:211]
	s_waitcnt lgkmcnt(6)
; #define SB() __builtin_amdgcn_sched_barrier(0)
; #define EXPACK(sc_, rbq_, p0_, p1_) do { float ps_ = 0.f; \
;                 _Pragma("unroll") for (int r = 0; r < 16; ++r) { sc_[r] = __builtin_amdgcn_exp2f(SHIFT ? sc_[r] - bound2 : sc_[r]); ps_ += sc_[r]; } \
;                 lsum[rbq_] += ps_; p0_ = pack8(sc_, 0); p1_ = pack8(sc_, 1); } while (0)
; #define BLOAD(B_, ks_) do { asm volatile("" : "+v"(v0l)); _Pragma("unroll") for (int cb = 0; cb < 4; ++cb) B_[cb] = BFRAG(ks_, cb); SB(); } while (0)
; #define PVMMA(B_, pA_, pB_) do { _Pragma("unroll") for (int cb = 0; cb < 4; ++cb) { o[0][cb] = MFMA32(pA_, B_[cb], o[0][cb]); o[1][cb] = MFMA32(pB_, B_[cb], o[1][cb]); } } while (0)
; template <bool SHIFT> DI void phase_attn2(const Params& p, const Grp& G, int layer, LAS unsigned char* lds, int tid, int wave, int lane, int vcu, bool dry) {
;     ...
;                 CHAIN(s0, 0, 0, true, true); CHAIN(s1, 0, 1, false, true);
;                 EXPACK(s0, 0, pa00, pa01); EXPACK(s1, 1, pa10, pa11);
;                 SB();
;                 CHAIN(s1, 1, 1, true, false); CHAIN(s0, 1, 0, false, true);
;                 bf16x8 pb00, pb01, pb10, pb11; bf16x8 B[4];
;                 BLOAD(B, 0);
;                 PVMMA(B, pa00, pa10); EXPACK(s0, 0, pb00, pb01);
;                 SB();
;                 BLOAD(B, 1);
;                 PVMMA(B, pa01, pa11); EXPACK(s1, 1, pb10, pb11);
;                 SB();
;                 BLOAD(B, 2);
;                 PVMMA(B, pb00, pb10);
;                 SB();
;                 BLOAD(B, 3);
;                 PVMMA(B, pb01, pb11);
;                 SB();
;             }
;     ...
;             asm volatile("s_waitcnt vmcnt(0)" ::: "memory");
;             __syncthreads();
	v_mfma_f32_32x32x16_bf16 v[112:127], v[132:135], v[160:163], v[112:127]
	v_add_f32_e64 v128, v208, v128
	v_add_f32_e64 v129, v209, v129
	v_exp_f32_e32 v177, v140
	v_pk_add_f32 v[128:129], v[206:207], v[128:129]
	v_exp_f32_e32 v183, v141
	v_pk_add_f32 v[128:129], v[204:205], v[128:129]
	v_exp_f32_e32 v181, v142
	v_pk_add_f32 v[128:129], v[202:203], v[128:129]
	s_waitcnt lgkmcnt(4)
	v_mfma_f32_32x32x16_bf16 v[96:111], v[132:135], v[156:159], v[96:111]
	v_exp_f32_e32 v185, v143
	v_pk_add_f32 v[128:129], v[200:201], v[128:129]
	v_cvt_pk_bf16_f32 v147, v166, v170
	v_pk_add_f32 v[128:129], v[198:199], v[128:129]
	v_cvt_pk_bf16_f32 v130, v176, v182
	v_pk_add_f32 v[128:129], v[196:197], v[128:129]
	v_cvt_pk_bf16_f32 v131, v180, v184
	s_waitcnt lgkmcnt(2)
	v_mfma_f32_32x32x16_bf16 v[80:95], v[132:135], v[152:155], v[80:95]
	v_add_f32_e64 v128, v190, v128
	v_add_f32_e64 v129, v191, v129
	v_add_f32_e64 v140, v164, v128
	v_add_f32_e64 v141, v165, v129
	v_cvt_pk_bf16_f32 v128, v168, v174
	v_cvt_pk_bf16_f32 v129, v172, v178
	s_waitcnt lgkmcnt(0)
	v_mfma_f32_32x32x16_bf16 v[64:79], v[132:135], v[148:151], v[64:79]
	v_add_f32_e64 v132, v166, v186
	v_add_f32_e64 v133, v167, v187
	v_cvt_pk_bf16_f32 v134, v227, v228
	v_add_f32_e64 v132, v170, v132
	v_add_f32_e64 v133, v171, v133
	v_cvt_pk_bf16_f32 v135, v167, v171
	v_pk_add_f32 v[132:133], v[168:169], v[132:133]
	s_nop 0
	v_pk_add_f32 v[132:133], v[174:175], v[132:133]
	v_mfma_f32_32x32x16_bf16 v[0:15], v[136:139], v[160:163], v[0:15]
	v_add_f32_e64 v132, v172, v132
	v_add_f32_e64 v133, v173, v133
	v_add_f32_e64 v132, v178, v132
	v_add_f32_e64 v133, v179, v133
	v_add_f32_e64 v132, v176, v132
	v_add_f32_e64 v133, v177, v133
	v_pk_add_f32 v[132:133], v[182:183], v[132:133]
	v_mfma_f32_32x32x16_bf16 v[16:31], v[136:139], v[156:159], v[16:31]
	v_add_f32_e64 v132, v180, v132
	v_add_f32_e64 v133, v181, v133
	v_add_f32_e64 v142, v184, v132
	v_add_f32_e64 v143, v185, v133
	v_cvt_pk_bf16_f32 v132, v223, v224
	v_cvt_pk_bf16_f32 v133, v225, v226
	v_mfma_f32_32x32x16_bf16 v[32:47], v[136:139], v[152:155], v[32:47]
	v_mfma_f32_32x32x16_bf16 v[48:63], v[136:139], v[148:151], v[48:63]
	v_cvt_pk_bf16_f32 v136, v169, v175
	v_cvt_pk_bf16_f32 v137, v173, v179
	v_cvt_pk_bf16_f32 v138, v177, v183
	v_cvt_pk_bf16_f32 v139, v181, v185
	s_nop 0
	ds_read_b64_tr_b16 v[148:149], v218 offset:57344
	ds_read_b64_tr_b16 v[150:151], v239 offset:59392
	ds_read_b64_tr_b16 v[152:153], v240 offset:57344
	ds_read_b64_tr_b16 v[154:155], v241 offset:59392
	ds_read_b64_tr_b16 v[156:157], v248 offset:57344
	ds_read_b64_tr_b16 v[158:159], v249 offset:59392
	ds_read_b64_tr_b16 v[160:161], v250 offset:57344
	ds_read_b64_tr_b16 v[162:163], v251 offset:59392
	s_waitcnt lgkmcnt(6)
	v_mfma_f32_32x32x16_bf16 v[112:127], v[144:147], v[148:151], v[112:127]
	v_add_f32_e64 v164, v140, v142
	v_add_f32_e64 v165, v141, v143
	v_mfma_f32_32x32x16_bf16 v[0:15], v[132:135], v[148:151], v[0:15]
	s_waitcnt lgkmcnt(4)
	v_mfma_f32_32x32x16_bf16 v[96:111], v[144:147], v[152:155], v[96:111]
	v_mfma_f32_32x32x16_bf16 v[16:31], v[132:135], v[152:155], v[16:31]
	s_waitcnt lgkmcnt(2)
	v_mfma_f32_32x32x16_bf16 v[80:95], v[144:147], v[156:159], v[80:95]
	v_mfma_f32_32x32x16_bf16 v[32:47], v[132:135], v[156:159], v[32:47]
	s_waitcnt lgkmcnt(0)
	v_mfma_f32_32x32x16_bf16 v[64:79], v[144:147], v[160:163], v[64:79]
	v_mfma_f32_32x32x16_bf16 v[48:63], v[132:135], v[160:163], v[48:63]
	s_nop 0
	ds_read_b64_tr_b16 v[132:133], v218 offset:61440
	ds_read_b64_tr_b16 v[134:135], v239 offset:63488
	ds_read_b64_tr_b16 v[140:141], v240 offset:61440
	ds_read_b64_tr_b16 v[142:143], v241 offset:63488
	ds_read_b64_tr_b16 v[144:145], v248 offset:61440
	ds_read_b64_tr_b16 v[146:147], v249 offset:63488
	ds_read_b64_tr_b16 v[148:149], v250 offset:61440
	ds_read_b64_tr_b16 v[150:151], v251 offset:63488
	s_waitcnt lgkmcnt(6)
	v_mfma_f32_32x32x16_bf16 v[112:127], v[128:131], v[132:135], v[112:127]
	v_mfma_f32_32x32x16_bf16 v[0:15], v[136:139], v[132:135], v[0:15]
	ds_read_b128 v[132:135], v222
	ds_read_b128 v[228:231], v222 offset:3072
	s_waitcnt lgkmcnt(6)
	v_mfma_f32_32x32x16_bf16 v[96:111], v[128:131], v[140:143], v[96:111]
	v_mfma_f32_32x32x16_bf16 v[16:31], v[136:139], v[140:143], v[16:31]
	ds_read_b128 v[140:143], v222 offset:2048
	s_waitcnt lgkmcnt(5)
	v_mfma_f32_32x32x16_bf16 v[80:95], v[128:131], v[144:147], v[80:95]
	v_mfma_f32_32x32x16_bf16 v[32:47], v[136:139], v[144:147], v[32:47]
	s_waitcnt lgkmcnt(3)
	v_mfma_f32_32x32x16_bf16 v[64:79], v[128:131], v[148:151], v[64:79]
	v_mfma_f32_32x32x16_bf16 v[48:63], v[136:139], v[148:151], v[48:63]
	ds_read_b128 v[136:139], v222 offset:1024
	ds_read_b128 v[174:177], v222 offset:4096
	ds_read_b128 v[178:181], v222 offset:5120
	ds_read_b128 v[182:185], v222 offset:6144
	ds_read_b128 v[224:227], v222 offset:7168
	s_waitcnt vmcnt(0)
	s_add_u32 s30, s30, 0x50000
	s_addc_u32 s31, s31, 0
	s_cmp_eq_u32 s45, s38
	s_mov_b32 s8, s39
	s_barrier
	s_cbranch_scc1 .LBB0_383
	s_branch .LBB0_379
